# H+A+Q+P2+S + neighbourhood-attention bias: 128 exec-masked ds_read/wait/add diamonds replaced by batched unconditional LDS reads + v_add + v_cndmask
# speedup vs baseline: 1.0088x; 1.0029x over previous
; #define LAS __attribute__((address_space(3)))
; #define SBAR() __builtin_amdgcn_sched_barrier(0)
; __device__ __forceinline__ void apply_mask(f32x16& p0, f32x16& p1, const Mask& M, int t, int hi) {
;     ...
;         const int kr = M.rk0 + t; int r0q = M.qr - 4; r0q = r0q < 0 ? 0 : (r0q > 120 ? 120 : r0q);
;         const bool rowok = (kr >= r0q) && (kr < r0q + 8);
;         if (!rowok) return;
;         int dr = kr - M.qr + 7; dr = dr < 0 ? 0 : (dr > 14 ? 14 : dr);
;         int c0 = M.qc - 8; c0 = c0 < 0 ? 0 : (c0 > 48 ? 48 : c0);
;         const int c0h = c0 - 4 * hi;
;         const LAS float* tb = M.rpb + dr * 31 + (15 - M.qc) + 4 * hi;
; #pragma unroll
;         for (int r = 0; r < 16; ++r) { const float b0 = tb[CR(r)]; p0[r] = ((unsigned)(CR(r) - c0h) < 16u) ? p0[r] + b0 : NEG; }
;         SBAR();
; #pragma unroll
;         for (int r = 0; r < 16; ++r) { const float b1 = tb[CR(r) + 32]; p1[r] = ((unsigned)(CR(r) + 32 - c0h) < 16u) ? p1[r] + b1 : NEG; }
.LBB0_959:
	s_add_i32 s10, s29, s35
	s_add_i32 s21, s10, -7
	s_cmp_ge_u32 s21, s27
	s_cselect_b64 s[10:11], -1, 0
	s_cmp_lt_u32 s21, s34
	s_cselect_b64 s[36:37], -1, 0
	s_and_b64 s[10:11], s[10:11], s[36:37]
	s_andn2_b64 vcc, exec, s[10:11]
	s_cbranch_vccnz .LBB0_1025
	s_add_i32 s10, s25, s35
	s_add_i32 s10, s10, -7
	v_med3_i32 v17, s10, -7, 7
	s_movk_i32 s10, 0x7c
	v_mul_lo_u32 v17, v17, s10
	v_mov_b32_e32 v131, 0xff800000
	v_add_u32_e32 v17, v235, v17
	ds_read_b32 v130, v17 offset:868
	ds_read_b32 v131, v17 offset:872
	ds_read_b32 v132, v17 offset:876
	ds_read_b32 v133, v17 offset:880
	ds_read_b32 v134, v17 offset:900
	ds_read_b32 v135, v17 offset:904
	ds_read_b32 v136, v17 offset:908
	ds_read_b32 v137, v17 offset:912
	ds_read_b32 v138, v17 offset:932
	ds_read_b32 v139, v17 offset:936
	ds_read_b32 v140, v17 offset:940
	ds_read_b32 v141, v17 offset:944
	ds_read_b32 v142, v17 offset:964
	ds_read_b32 v143, v17 offset:968
	ds_read_b32 v144, v17 offset:972
	ds_read_b32 v145, v17 offset:976
	s_waitcnt lgkmcnt(15)
	v_add_f32_e32 v130, v114, v130
	v_cndmask_b32_e64 v130, v18, v130, s[40:41]
	s_waitcnt lgkmcnt(14)
	v_add_f32_e32 v131, v115, v131
	v_cndmask_b32_e64 v131, v18, v131, s[42:43]
	s_waitcnt lgkmcnt(13)
	v_add_f32_e32 v132, v116, v132
	v_cndmask_b32_e64 v132, v18, v132, s[44:45]
	s_waitcnt lgkmcnt(12)
	v_add_f32_e32 v133, v117, v133
	v_cndmask_b32_e64 v133, v18, v133, s[46:47]
	s_waitcnt lgkmcnt(11)
	v_add_f32_e32 v134, v118, v134
	v_cndmask_b32_e64 v134, v18, v134, s[48:49]
	s_waitcnt lgkmcnt(10)
	v_add_f32_e32 v135, v119, v135
	v_cndmask_b32_e64 v135, v18, v135, s[50:51]
	s_waitcnt lgkmcnt(9)
	v_add_f32_e32 v136, v120, v136
	v_cndmask_b32_e64 v136, v18, v136, s[52:53]
	s_waitcnt lgkmcnt(8)
	v_add_f32_e32 v137, v121, v137
	v_cndmask_b32_e64 v137, v18, v137, s[54:55]
	s_waitcnt lgkmcnt(7)
	v_add_f32_e32 v138, v122, v138
	v_cndmask_b32_e64 v138, v18, v138, s[56:57]
	s_waitcnt lgkmcnt(6)
	v_add_f32_e32 v139, v123, v139
	v_cndmask_b32_e64 v139, v18, v139, s[58:59]
	s_waitcnt lgkmcnt(5)
	v_add_f32_e32 v140, v124, v140
	v_cndmask_b32_e64 v140, v18, v140, s[60:61]
	s_waitcnt lgkmcnt(4)
	v_add_f32_e32 v141, v125, v141
	v_cndmask_b32_e64 v141, v18, v141, s[62:63]
	s_waitcnt lgkmcnt(3)
	v_add_f32_e32 v142, v126, v142
	v_cndmask_b32_e64 v142, v18, v142, s[64:65]
	s_waitcnt lgkmcnt(2)
	v_add_f32_e32 v143, v127, v143
	v_cndmask_b32_e64 v143, v18, v143, s[66:67]
	s_waitcnt lgkmcnt(1)
	v_add_f32_e32 v144, v128, v144
	v_cndmask_b32_e64 v144, v18, v144, s[68:69]
	s_waitcnt lgkmcnt(0)
	v_add_f32_e32 v145, v129, v145
	v_cndmask_b32_e64 v145, v18, v145, s[70:71]
	ds_read_b32 v114, v17 offset:996
	ds_read_b32 v115, v17 offset:1000
	ds_read_b32 v116, v17 offset:1004
	ds_read_b32 v117, v17 offset:1008
	ds_read_b32 v118, v17 offset:1028
	ds_read_b32 v119, v17 offset:1032
	ds_read_b32 v120, v17 offset:1036
	ds_read_b32 v121, v17 offset:1040
	ds_read_b32 v122, v17 offset:1060
	ds_read_b32 v123, v17 offset:1064
	ds_read_b32 v124, v17 offset:1068
	ds_read_b32 v125, v17 offset:1072
	ds_read_b32 v126, v17 offset:1092
	ds_read_b32 v127, v17 offset:1096
	ds_read_b32 v128, v17 offset:1100
	ds_read_b32 v129, v17 offset:1104
	s_waitcnt lgkmcnt(15)
	v_add_f32_e32 v114, v98, v114
	v_cndmask_b32_e64 v114, v18, v114, s[72:73]
	s_waitcnt lgkmcnt(14)
	v_add_f32_e32 v115, v99, v115
	v_cndmask_b32_e64 v115, v18, v115, s[74:75]
	s_waitcnt lgkmcnt(13)
	v_add_f32_e32 v116, v100, v116
	v_cndmask_b32_e64 v116, v18, v116, s[76:77]
	s_waitcnt lgkmcnt(12)
	v_add_f32_e32 v117, v101, v117
	v_cndmask_b32_e64 v117, v18, v117, s[78:79]
	s_waitcnt lgkmcnt(11)
	v_add_f32_e32 v118, v102, v118
	v_cndmask_b32_e64 v118, v18, v118, s[80:81]
	s_waitcnt lgkmcnt(10)
	v_add_f32_e32 v119, v103, v119
	v_cndmask_b32_e64 v119, v18, v119, s[82:83]
	s_waitcnt lgkmcnt(9)
	v_add_f32_e32 v120, v104, v120
	v_cndmask_b32_e64 v120, v18, v120, s[84:85]
	s_waitcnt lgkmcnt(8)
	v_add_f32_e32 v121, v105, v121
	v_cndmask_b32_e64 v121, v18, v121, s[86:87]
	s_waitcnt lgkmcnt(7)
	v_add_f32_e32 v122, v106, v122
	v_cndmask_b32_e64 v122, v18, v122, s[88:89]
	s_waitcnt lgkmcnt(6)
	v_add_f32_e32 v123, v107, v123
	v_cndmask_b32_e64 v123, v18, v123, s[90:91]
	s_waitcnt lgkmcnt(5)
	v_add_f32_e32 v124, v108, v124
	v_cndmask_b32_e64 v124, v18, v124, s[92:93]
	s_waitcnt lgkmcnt(4)
	v_add_f32_e32 v125, v109, v125
	v_cndmask_b32_e64 v125, v18, v125, s[94:95]
	s_waitcnt lgkmcnt(3)
	v_add_f32_e32 v126, v110, v126
	v_cndmask_b32_e64 v126, v18, v126, s[96:97]
	s_waitcnt lgkmcnt(2)
	v_add_f32_e32 v127, v111, v127
	v_cndmask_b32_e64 v127, v18, v127, s[2:3]
	s_waitcnt lgkmcnt(1)
	v_add_f32_e32 v128, v112, v128
	v_cndmask_b32_e64 v128, v18, v128, s[4:5]
	s_waitcnt lgkmcnt(0)
	v_add_f32_e32 v129, v113, v129
	v_cndmask_b32_e64 v129, v18, v129, s[6:7]
	v_mov_b64_e32 v[98:99], v[114:115]
	v_mov_b64_e32 v[100:101], v[116:117]
	v_mov_b64_e32 v[102:103], v[118:119]
	v_mov_b64_e32 v[104:105], v[120:121]
	v_mov_b64_e32 v[106:107], v[122:123]
	v_mov_b64_e32 v[108:109], v[124:125]
	v_mov_b64_e32 v[110:111], v[126:127]
	v_mov_b64_e32 v[112:113], v[128:129]
	v_mov_b64_e32 v[114:115], v[130:131]
	v_mov_b64_e32 v[116:117], v[132:133]
	v_mov_b64_e32 v[118:119], v[134:135]
	v_mov_b64_e32 v[120:121], v[136:137]
	v_mov_b64_e32 v[122:123], v[138:139]
	v_mov_b64_e32 v[124:125], v[140:141]
	v_mov_b64_e32 v[126:127], v[142:143]
	v_mov_b64_e32 v[128:129], v[144:145]

; #define LAS __attribute__((address_space(3)))
; #define SBAR() __builtin_amdgcn_sched_barrier(0)
; __device__ __forceinline__ void apply_mask(f32x16& p0, f32x16& p1, const Mask& M, int t, int hi) {
;     ...
;         const int kr = M.rk0 + t; int r0q = M.qr - 4; r0q = r0q < 0 ? 0 : (r0q > 120 ? 120 : r0q);
;         const bool rowok = (kr >= r0q) && (kr < r0q + 8);
;         if (!rowok) return;
;         int dr = kr - M.qr + 7; dr = dr < 0 ? 0 : (dr > 14 ? 14 : dr);
;         int c0 = M.qc - 8; c0 = c0 < 0 ? 0 : (c0 > 48 ? 48 : c0);
;         const int c0h = c0 - 4 * hi;
;         const LAS float* tb = M.rpb + dr * 31 + (15 - M.qc) + 4 * hi;
; #pragma unroll
;         for (int r = 0; r < 16; ++r) { const float b0 = tb[CR(r)]; p0[r] = ((unsigned)(CR(r) - c0h) < 16u) ? p0[r] + b0 : NEG; }
;         SBAR();
; #pragma unroll
;         for (int r = 0; r < 16; ++r) { const float b1 = tb[CR(r) + 32]; p1[r] = ((unsigned)(CR(r) + 32 - c0h) < 16u) ? p1[r] + b1 : NEG; }
.LBB0_1041:
	s_add_i32 s8, s29, s35
	s_add_i32 s10, s8, -6
	s_cmp_ge_u32 s10, s27
	s_cselect_b64 s[8:9], -1, 0
	s_cmp_lt_u32 s10, s34
	s_cselect_b64 s[10:11], -1, 0
	s_and_b64 s[8:9], s[8:9], s[10:11]
	s_andn2_b64 vcc, exec, s[8:9]
	s_cbranch_vccnz .LBB0_1107
	s_add_i32 s8, s25, s35
	s_add_i32 s8, s8, -6
	v_med3_i32 v19, s8, -7, 7
	s_movk_i32 s8, 0x7c
	v_mul_lo_u32 v19, v19, s8
	v_mov_b32_e32 v99, 0xff800000
	v_add_u32_e32 v19, v235, v19
	ds_read_b32 v98, v19 offset:868
	ds_read_b32 v99, v19 offset:872
	ds_read_b32 v100, v19 offset:876
	ds_read_b32 v101, v19 offset:880
	ds_read_b32 v102, v19 offset:900
	ds_read_b32 v103, v19 offset:904
	ds_read_b32 v104, v19 offset:908
	ds_read_b32 v105, v19 offset:912
	ds_read_b32 v106, v19 offset:932
	ds_read_b32 v107, v19 offset:936
	ds_read_b32 v108, v19 offset:940
	ds_read_b32 v109, v19 offset:944
	ds_read_b32 v110, v19 offset:964
	ds_read_b32 v111, v19 offset:968
	ds_read_b32 v112, v19 offset:972
	ds_read_b32 v113, v19 offset:976
	s_waitcnt lgkmcnt(15)
	v_add_f32_e32 v98, v130, v98
	v_cndmask_b32_e64 v98, v18, v98, s[40:41]
	s_waitcnt lgkmcnt(14)
	v_add_f32_e32 v99, v131, v99
	v_cndmask_b32_e64 v99, v18, v99, s[42:43]
	s_waitcnt lgkmcnt(13)
	v_add_f32_e32 v100, v132, v100
	v_cndmask_b32_e64 v100, v18, v100, s[44:45]
	s_waitcnt lgkmcnt(12)
	v_add_f32_e32 v101, v133, v101
	v_cndmask_b32_e64 v101, v18, v101, s[46:47]
	s_waitcnt lgkmcnt(11)
	v_add_f32_e32 v102, v134, v102
	v_cndmask_b32_e64 v102, v18, v102, s[48:49]
	s_waitcnt lgkmcnt(10)
	v_add_f32_e32 v103, v135, v103
	v_cndmask_b32_e64 v103, v18, v103, s[50:51]
	s_waitcnt lgkmcnt(9)
	v_add_f32_e32 v104, v136, v104
	v_cndmask_b32_e64 v104, v18, v104, s[52:53]
	s_waitcnt lgkmcnt(8)
	v_add_f32_e32 v105, v137, v105
	v_cndmask_b32_e64 v105, v18, v105, s[54:55]
	s_waitcnt lgkmcnt(7)
	v_add_f32_e32 v106, v138, v106
	v_cndmask_b32_e64 v106, v18, v106, s[56:57]
	s_waitcnt lgkmcnt(6)
	v_add_f32_e32 v107, v139, v107
	v_cndmask_b32_e64 v107, v18, v107, s[58:59]
	s_waitcnt lgkmcnt(5)
	v_add_f32_e32 v108, v140, v108
	v_cndmask_b32_e64 v108, v18, v108, s[60:61]
	s_waitcnt lgkmcnt(4)
	v_add_f32_e32 v109, v141, v109
	v_cndmask_b32_e64 v109, v18, v109, s[62:63]
	s_waitcnt lgkmcnt(3)
	v_add_f32_e32 v110, v142, v110
	v_cndmask_b32_e64 v110, v18, v110, s[64:65]
	s_waitcnt lgkmcnt(2)
	v_add_f32_e32 v111, v143, v111
	v_cndmask_b32_e64 v111, v18, v111, s[66:67]
	s_waitcnt lgkmcnt(1)
	v_add_f32_e32 v112, v144, v112
	v_cndmask_b32_e64 v112, v18, v112, s[68:69]
	s_waitcnt lgkmcnt(0)
	v_add_f32_e32 v113, v145, v113
	v_cndmask_b32_e64 v113, v18, v113, s[70:71]
	ds_read_b32 v130, v19 offset:996
	ds_read_b32 v131, v19 offset:1000
	ds_read_b32 v132, v19 offset:1004
	ds_read_b32 v133, v19 offset:1008
	ds_read_b32 v134, v19 offset:1028
	ds_read_b32 v135, v19 offset:1032
	ds_read_b32 v136, v19 offset:1036
	ds_read_b32 v137, v19 offset:1040
	ds_read_b32 v138, v19 offset:1060
	ds_read_b32 v139, v19 offset:1064
	ds_read_b32 v140, v19 offset:1068
	ds_read_b32 v141, v19 offset:1072
	ds_read_b32 v142, v19 offset:1092
	ds_read_b32 v143, v19 offset:1096
	ds_read_b32 v144, v19 offset:1100
	ds_read_b32 v145, v19 offset:1104
	s_waitcnt lgkmcnt(15)
	v_add_f32_e32 v130, v114, v130
	v_cndmask_b32_e64 v130, v18, v130, s[72:73]
	s_waitcnt lgkmcnt(14)
	v_add_f32_e32 v131, v115, v131
	v_cndmask_b32_e64 v131, v18, v131, s[74:75]
	s_waitcnt lgkmcnt(13)
	v_add_f32_e32 v132, v116, v132
	v_cndmask_b32_e64 v132, v18, v132, s[76:77]
	s_waitcnt lgkmcnt(12)
	v_add_f32_e32 v133, v117, v133
	v_cndmask_b32_e64 v133, v18, v133, s[78:79]
	s_waitcnt lgkmcnt(11)
	v_add_f32_e32 v134, v118, v134
	v_cndmask_b32_e64 v134, v18, v134, s[80:81]
	s_waitcnt lgkmcnt(10)
	v_add_f32_e32 v135, v119, v135
	v_cndmask_b32_e64 v135, v18, v135, s[82:83]
	s_waitcnt lgkmcnt(9)
	v_add_f32_e32 v136, v120, v136
	v_cndmask_b32_e64 v136, v18, v136, s[84:85]
	s_waitcnt lgkmcnt(8)
	v_add_f32_e32 v137, v121, v137
	v_cndmask_b32_e64 v137, v18, v137, s[86:87]
	s_waitcnt lgkmcnt(7)
	v_add_f32_e32 v138, v122, v138
	v_cndmask_b32_e64 v138, v18, v138, s[88:89]
	s_waitcnt lgkmcnt(6)
	v_add_f32_e32 v139, v123, v139
	v_cndmask_b32_e64 v139, v18, v139, s[90:91]
	s_waitcnt lgkmcnt(5)
	v_add_f32_e32 v140, v124, v140
	v_cndmask_b32_e64 v140, v18, v140, s[92:93]
	s_waitcnt lgkmcnt(4)
	v_add_f32_e32 v141, v125, v141
	v_cndmask_b32_e64 v141, v18, v141, s[94:95]
	s_waitcnt lgkmcnt(3)
	v_add_f32_e32 v142, v126, v142
	v_cndmask_b32_e64 v142, v18, v142, s[96:97]
	s_waitcnt lgkmcnt(2)
	v_add_f32_e32 v143, v127, v143
	v_cndmask_b32_e64 v143, v18, v143, s[2:3]
	s_waitcnt lgkmcnt(1)
	v_add_f32_e32 v144, v128, v144
	v_cndmask_b32_e64 v144, v18, v144, s[4:5]
	s_waitcnt lgkmcnt(0)
	v_add_f32_e32 v145, v129, v145
	v_cndmask_b32_e64 v145, v18, v145, s[6:7]
	v_mov_b64_e32 v[114:115], v[130:131]
	v_mov_b64_e32 v[116:117], v[132:133]
	v_mov_b64_e32 v[118:119], v[134:135]
	v_mov_b64_e32 v[120:121], v[136:137]
	v_mov_b64_e32 v[122:123], v[138:139]
	v_mov_b64_e32 v[124:125], v[140:141]
	v_mov_b64_e32 v[126:127], v[142:143]
	v_mov_b64_e32 v[128:129], v[144:145]
	v_mov_b64_e32 v[144:145], v[112:113]
	v_mov_b64_e32 v[142:143], v[110:111]
	v_mov_b64_e32 v[140:141], v[108:109]
	v_mov_b64_e32 v[138:139], v[106:107]
	v_mov_b64_e32 v[136:137], v[104:105]
	v_mov_b64_e32 v[134:135], v[102:103]
	v_mov_b64_e32 v[132:133], v[100:101]
	v_mov_b64_e32 v[130:131], v[98:99]

; #define LAS __attribute__((address_space(3)))
; #define SBAR() __builtin_amdgcn_sched_barrier(0)
; __device__ __forceinline__ void apply_mask(f32x16& p0, f32x16& p1, const Mask& M, int t, int hi) {
;     ...
;         const int kr = M.rk0 + t; int r0q = M.qr - 4; r0q = r0q < 0 ? 0 : (r0q > 120 ? 120 : r0q);
;         const bool rowok = (kr >= r0q) && (kr < r0q + 8);
;         if (!rowok) return;
;         int dr = kr - M.qr + 7; dr = dr < 0 ? 0 : (dr > 14 ? 14 : dr);
;         int c0 = M.qc - 8; c0 = c0 < 0 ? 0 : (c0 > 48 ? 48 : c0);
;         const int c0h = c0 - 4 * hi;
;         const LAS float* tb = M.rpb + dr * 31 + (15 - M.qc) + 4 * hi;
; #pragma unroll
;         for (int r = 0; r < 16; ++r) { const float b0 = tb[CR(r)]; p0[r] = ((unsigned)(CR(r) - c0h) < 16u) ? p0[r] + b0 : NEG; }
;         SBAR();
; #pragma unroll
;         for (int r = 0; r < 16; ++r) { const float b1 = tb[CR(r) + 32]; p1[r] = ((unsigned)(CR(r) + 32 - c0h) < 16u) ? p1[r] + b1 : NEG; }
.LBB0_2493:
	s_add_i32 s8, s24, s26
	s_add_i32 s15, s8, -7
	s_cmp_ge_u32 s15, s34
	s_cselect_b64 s[8:9], -1, 0
	s_cmp_lt_u32 s15, s35
	s_cselect_b64 s[22:23], -1, 0
	s_and_b64 s[8:9], s[8:9], s[22:23]
	s_andn2_b64 vcc, exec, s[8:9]
	s_cbranch_vccnz .LBB0_2559
	s_add_i32 s8, s0, s26
	s_add_i32 s8, s8, -7
	v_med3_i32 v17, s8, -7, 7
	s_movk_i32 s8, 0x7c
	v_mul_lo_u32 v17, v17, s8
	v_mov_b32_e32 v131, 0xff800000
	v_add_u32_e32 v17, v235, v17
	ds_read_b32 v130, v17 offset:868
	ds_read_b32 v131, v17 offset:872
	ds_read_b32 v132, v17 offset:876
	ds_read_b32 v133, v17 offset:880
	ds_read_b32 v134, v17 offset:900
	ds_read_b32 v135, v17 offset:904
	ds_read_b32 v136, v17 offset:908
	ds_read_b32 v137, v17 offset:912
	ds_read_b32 v138, v17 offset:932
	ds_read_b32 v139, v17 offset:936
	ds_read_b32 v140, v17 offset:940
	ds_read_b32 v141, v17 offset:944
	ds_read_b32 v142, v17 offset:964
	ds_read_b32 v143, v17 offset:968
	ds_read_b32 v144, v17 offset:972
	ds_read_b32 v145, v17 offset:976
	s_waitcnt lgkmcnt(15)
	v_add_f32_e32 v130, v114, v130
	v_cndmask_b32_e64 v130, v18, v130, s[38:39]
	s_waitcnt lgkmcnt(14)
	v_add_f32_e32 v131, v115, v131
	v_cndmask_b32_e64 v131, v18, v131, s[40:41]
	s_waitcnt lgkmcnt(13)
	v_add_f32_e32 v132, v116, v132
	v_cndmask_b32_e64 v132, v18, v132, s[42:43]
	s_waitcnt lgkmcnt(12)
	v_add_f32_e32 v133, v117, v133
	v_cndmask_b32_e64 v133, v18, v133, s[44:45]
	s_waitcnt lgkmcnt(11)
	v_add_f32_e32 v134, v118, v134
	v_cndmask_b32_e64 v134, v18, v134, s[46:47]
	s_waitcnt lgkmcnt(10)
	v_add_f32_e32 v135, v119, v135
	v_cndmask_b32_e64 v135, v18, v135, s[48:49]
	s_waitcnt lgkmcnt(9)
	v_add_f32_e32 v136, v120, v136
	v_cndmask_b32_e64 v136, v18, v136, s[50:51]
	s_waitcnt lgkmcnt(8)
	v_add_f32_e32 v137, v121, v137
	v_cndmask_b32_e64 v137, v18, v137, s[52:53]
	s_waitcnt lgkmcnt(7)
	v_add_f32_e32 v138, v122, v138
	v_cndmask_b32_e64 v138, v18, v138, s[54:55]
	s_waitcnt lgkmcnt(6)
	v_add_f32_e32 v139, v123, v139
	v_cndmask_b32_e64 v139, v18, v139, s[56:57]
	s_waitcnt lgkmcnt(5)
	v_add_f32_e32 v140, v124, v140
	v_cndmask_b32_e64 v140, v18, v140, s[58:59]
	s_waitcnt lgkmcnt(4)
	v_add_f32_e32 v141, v125, v141
	v_cndmask_b32_e64 v141, v18, v141, s[60:61]
	s_waitcnt lgkmcnt(3)
	v_add_f32_e32 v142, v126, v142
	v_cndmask_b32_e64 v142, v18, v142, s[62:63]
	s_waitcnt lgkmcnt(2)
	v_add_f32_e32 v143, v127, v143
	v_cndmask_b32_e64 v143, v18, v143, s[64:65]
	s_waitcnt lgkmcnt(1)
	v_add_f32_e32 v144, v128, v144
	v_cndmask_b32_e64 v144, v18, v144, s[66:67]
	s_waitcnt lgkmcnt(0)
	v_add_f32_e32 v145, v129, v145
	v_cndmask_b32_e64 v145, v18, v145, s[68:69]
	ds_read_b32 v114, v17 offset:996
	ds_read_b32 v115, v17 offset:1000
	ds_read_b32 v116, v17 offset:1004
	ds_read_b32 v117, v17 offset:1008
	ds_read_b32 v118, v17 offset:1028
	ds_read_b32 v119, v17 offset:1032
	ds_read_b32 v120, v17 offset:1036
	ds_read_b32 v121, v17 offset:1040
	ds_read_b32 v122, v17 offset:1060
	ds_read_b32 v123, v17 offset:1064
	ds_read_b32 v124, v17 offset:1068
	ds_read_b32 v125, v17 offset:1072
	ds_read_b32 v126, v17 offset:1092
	ds_read_b32 v127, v17 offset:1096
	ds_read_b32 v128, v17 offset:1100
	ds_read_b32 v129, v17 offset:1104
	s_waitcnt lgkmcnt(15)
	v_add_f32_e32 v114, v98, v114
	v_cndmask_b32_e64 v114, v18, v114, s[70:71]
	s_waitcnt lgkmcnt(14)
	v_add_f32_e32 v115, v99, v115
	v_cndmask_b32_e64 v115, v18, v115, s[72:73]
	s_waitcnt lgkmcnt(13)
	v_add_f32_e32 v116, v100, v116
	v_cndmask_b32_e64 v116, v18, v116, s[74:75]
	s_waitcnt lgkmcnt(12)
	v_add_f32_e32 v117, v101, v117
	v_cndmask_b32_e64 v117, v18, v117, s[76:77]
	s_waitcnt lgkmcnt(11)
	v_add_f32_e32 v118, v102, v118
	v_cndmask_b32_e64 v118, v18, v118, s[78:79]
	s_waitcnt lgkmcnt(10)
	v_add_f32_e32 v119, v103, v119
	v_cndmask_b32_e64 v119, v18, v119, s[80:81]
	s_waitcnt lgkmcnt(9)
	v_add_f32_e32 v120, v104, v120
	v_cndmask_b32_e64 v120, v18, v120, s[82:83]
	s_waitcnt lgkmcnt(8)
	v_add_f32_e32 v121, v105, v121
	v_cndmask_b32_e64 v121, v18, v121, s[84:85]
	s_waitcnt lgkmcnt(7)
	v_add_f32_e32 v122, v106, v122
	v_cndmask_b32_e64 v122, v18, v122, s[86:87]
	s_waitcnt lgkmcnt(6)
	v_add_f32_e32 v123, v107, v123
	v_cndmask_b32_e64 v123, v18, v123, s[88:89]
	s_waitcnt lgkmcnt(5)
	v_add_f32_e32 v124, v108, v124
	v_cndmask_b32_e64 v124, v18, v124, s[90:91]
	s_waitcnt lgkmcnt(4)
	v_add_f32_e32 v125, v109, v125
	v_cndmask_b32_e64 v125, v18, v125, s[92:93]
	s_waitcnt lgkmcnt(3)
	v_add_f32_e32 v126, v110, v126
	v_cndmask_b32_e64 v126, v18, v126, s[2:3]
	s_waitcnt lgkmcnt(2)
	v_add_f32_e32 v127, v111, v127
	v_cndmask_b32_e64 v127, v18, v127, s[4:5]
	s_waitcnt lgkmcnt(1)
	v_add_f32_e32 v128, v112, v128
	v_cndmask_b32_e64 v128, v18, v128, s[94:95]
	s_waitcnt lgkmcnt(0)
	v_add_f32_e32 v129, v113, v129
	v_cndmask_b32_e64 v129, v18, v129, s[6:7]
	v_mov_b64_e32 v[98:99], v[114:115]
	v_mov_b64_e32 v[100:101], v[116:117]
	v_mov_b64_e32 v[102:103], v[118:119]
	v_mov_b64_e32 v[104:105], v[120:121]
	v_mov_b64_e32 v[106:107], v[122:123]
	v_mov_b64_e32 v[108:109], v[124:125]
	v_mov_b64_e32 v[110:111], v[126:127]
	v_mov_b64_e32 v[112:113], v[128:129]
	v_mov_b64_e32 v[114:115], v[130:131]
	v_mov_b64_e32 v[116:117], v[132:133]
	v_mov_b64_e32 v[118:119], v[134:135]
	v_mov_b64_e32 v[120:121], v[136:137]
	v_mov_b64_e32 v[122:123], v[138:139]
	v_mov_b64_e32 v[124:125], v[140:141]
	v_mov_b64_e32 v[126:127], v[142:143]
	v_mov_b64_e32 v[128:129], v[144:145]

; #define LAS __attribute__((address_space(3)))
; #define SBAR() __builtin_amdgcn_sched_barrier(0)
; __device__ __forceinline__ void apply_mask(f32x16& p0, f32x16& p1, const Mask& M, int t, int hi) {
;     ...
;         const int kr = M.rk0 + t; int r0q = M.qr - 4; r0q = r0q < 0 ? 0 : (r0q > 120 ? 120 : r0q);
;         const bool rowok = (kr >= r0q) && (kr < r0q + 8);
;         if (!rowok) return;
;         int dr = kr - M.qr + 7; dr = dr < 0 ? 0 : (dr > 14 ? 14 : dr);
;         int c0 = M.qc - 8; c0 = c0 < 0 ? 0 : (c0 > 48 ? 48 : c0);
;         const int c0h = c0 - 4 * hi;
;         const LAS float* tb = M.rpb + dr * 31 + (15 - M.qc) + 4 * hi;
; #pragma unroll
;         for (int r = 0; r < 16; ++r) { const float b0 = tb[CR(r)]; p0[r] = ((unsigned)(CR(r) - c0h) < 16u) ? p0[r] + b0 : NEG; }
;         SBAR();
; #pragma unroll
;         for (int r = 0; r < 16; ++r) { const float b1 = tb[CR(r) + 32]; p1[r] = ((unsigned)(CR(r) + 32 - c0h) < 16u) ? p1[r] + b1 : NEG; }
.LBB0_2574:
	s_andn2_b64 vcc, exec, s[8:9]
	s_cbranch_vccnz .LBB0_2641
	s_add_i32 s8, s24, s26
	s_add_i32 s15, s8, -6
	s_cmp_ge_u32 s15, s34
	s_cselect_b64 s[8:9], -1, 0
	s_cmp_lt_u32 s15, s35
	s_cselect_b64 s[18:19], -1, 0
	s_and_b64 s[8:9], s[8:9], s[18:19]
	s_andn2_b64 vcc, exec, s[8:9]
	s_cbranch_vccnz .LBB0_2641
	s_add_i32 s8, s0, s26
	s_add_i32 s8, s8, -6
	v_med3_i32 v19, s8, -7, 7
	s_movk_i32 s8, 0x7c
	v_mul_lo_u32 v19, v19, s8
	v_mov_b32_e32 v99, 0xff800000
	v_add_u32_e32 v19, v235, v19
	ds_read_b32 v98, v19 offset:868
	ds_read_b32 v99, v19 offset:872
	ds_read_b32 v100, v19 offset:876
	ds_read_b32 v101, v19 offset:880
	ds_read_b32 v102, v19 offset:900
	ds_read_b32 v103, v19 offset:904
	ds_read_b32 v104, v19 offset:908
	ds_read_b32 v105, v19 offset:912
	ds_read_b32 v106, v19 offset:932
	ds_read_b32 v107, v19 offset:936
	ds_read_b32 v108, v19 offset:940
	ds_read_b32 v109, v19 offset:944
	ds_read_b32 v110, v19 offset:964
	ds_read_b32 v111, v19 offset:968
	ds_read_b32 v112, v19 offset:972
	ds_read_b32 v113, v19 offset:976
	s_waitcnt lgkmcnt(15)
	v_add_f32_e32 v98, v130, v98
	v_cndmask_b32_e64 v98, v18, v98, s[38:39]
	s_waitcnt lgkmcnt(14)
	v_add_f32_e32 v99, v131, v99
	v_cndmask_b32_e64 v99, v18, v99, s[40:41]
	s_waitcnt lgkmcnt(13)
	v_add_f32_e32 v100, v132, v100
	v_cndmask_b32_e64 v100, v18, v100, s[42:43]
	s_waitcnt lgkmcnt(12)
	v_add_f32_e32 v101, v133, v101
	v_cndmask_b32_e64 v101, v18, v101, s[44:45]
	s_waitcnt lgkmcnt(11)
	v_add_f32_e32 v102, v134, v102
	v_cndmask_b32_e64 v102, v18, v102, s[46:47]
	s_waitcnt lgkmcnt(10)
	v_add_f32_e32 v103, v135, v103
	v_cndmask_b32_e64 v103, v18, v103, s[48:49]
	s_waitcnt lgkmcnt(9)
	v_add_f32_e32 v104, v136, v104
	v_cndmask_b32_e64 v104, v18, v104, s[50:51]
	s_waitcnt lgkmcnt(8)
	v_add_f32_e32 v105, v137, v105
	v_cndmask_b32_e64 v105, v18, v105, s[52:53]
	s_waitcnt lgkmcnt(7)
	v_add_f32_e32 v106, v138, v106
	v_cndmask_b32_e64 v106, v18, v106, s[54:55]
	s_waitcnt lgkmcnt(6)
	v_add_f32_e32 v107, v139, v107
	v_cndmask_b32_e64 v107, v18, v107, s[56:57]
	s_waitcnt lgkmcnt(5)
	v_add_f32_e32 v108, v140, v108
	v_cndmask_b32_e64 v108, v18, v108, s[58:59]
	s_waitcnt lgkmcnt(4)
	v_add_f32_e32 v109, v141, v109
	v_cndmask_b32_e64 v109, v18, v109, s[60:61]
	s_waitcnt lgkmcnt(3)
	v_add_f32_e32 v110, v142, v110
	v_cndmask_b32_e64 v110, v18, v110, s[62:63]
	s_waitcnt lgkmcnt(2)
	v_add_f32_e32 v111, v143, v111
	v_cndmask_b32_e64 v111, v18, v111, s[64:65]
	s_waitcnt lgkmcnt(1)
	v_add_f32_e32 v112, v144, v112
	v_cndmask_b32_e64 v112, v18, v112, s[66:67]
	s_waitcnt lgkmcnt(0)
	v_add_f32_e32 v113, v145, v113
	v_cndmask_b32_e64 v113, v18, v113, s[68:69]
	ds_read_b32 v130, v19 offset:996
	ds_read_b32 v131, v19 offset:1000
	ds_read_b32 v132, v19 offset:1004
	ds_read_b32 v133, v19 offset:1008
	ds_read_b32 v134, v19 offset:1028
	ds_read_b32 v135, v19 offset:1032
	ds_read_b32 v136, v19 offset:1036
	ds_read_b32 v137, v19 offset:1040
	ds_read_b32 v138, v19 offset:1060
	ds_read_b32 v139, v19 offset:1064
	ds_read_b32 v140, v19 offset:1068
	ds_read_b32 v141, v19 offset:1072
	ds_read_b32 v142, v19 offset:1092
	ds_read_b32 v143, v19 offset:1096
	ds_read_b32 v144, v19 offset:1100
	ds_read_b32 v145, v19 offset:1104
	s_waitcnt lgkmcnt(15)
	v_add_f32_e32 v130, v114, v130
	v_cndmask_b32_e64 v130, v18, v130, s[70:71]
	s_waitcnt lgkmcnt(14)
	v_add_f32_e32 v131, v115, v131
	v_cndmask_b32_e64 v131, v18, v131, s[72:73]
	s_waitcnt lgkmcnt(13)
	v_add_f32_e32 v132, v116, v132
	v_cndmask_b32_e64 v132, v18, v132, s[74:75]
	s_waitcnt lgkmcnt(12)
	v_add_f32_e32 v133, v117, v133
	v_cndmask_b32_e64 v133, v18, v133, s[76:77]
	s_waitcnt lgkmcnt(11)
	v_add_f32_e32 v134, v118, v134
	v_cndmask_b32_e64 v134, v18, v134, s[78:79]
	s_waitcnt lgkmcnt(10)
	v_add_f32_e32 v135, v119, v135
	v_cndmask_b32_e64 v135, v18, v135, s[80:81]
	s_waitcnt lgkmcnt(9)
	v_add_f32_e32 v136, v120, v136
	v_cndmask_b32_e64 v136, v18, v136, s[82:83]
	s_waitcnt lgkmcnt(8)
	v_add_f32_e32 v137, v121, v137
	v_cndmask_b32_e64 v137, v18, v137, s[84:85]
	s_waitcnt lgkmcnt(7)
	v_add_f32_e32 v138, v122, v138
	v_cndmask_b32_e64 v138, v18, v138, s[86:87]
	s_waitcnt lgkmcnt(6)
	v_add_f32_e32 v139, v123, v139
	v_cndmask_b32_e64 v139, v18, v139, s[88:89]
	s_waitcnt lgkmcnt(5)
	v_add_f32_e32 v140, v124, v140
	v_cndmask_b32_e64 v140, v18, v140, s[90:91]
	s_waitcnt lgkmcnt(4)
	v_add_f32_e32 v141, v125, v141
	v_cndmask_b32_e64 v141, v18, v141, s[92:93]
	s_waitcnt lgkmcnt(3)
	v_add_f32_e32 v142, v126, v142
	v_cndmask_b32_e64 v142, v18, v142, s[2:3]
	s_waitcnt lgkmcnt(2)
	v_add_f32_e32 v143, v127, v143
	v_cndmask_b32_e64 v143, v18, v143, s[4:5]
	s_waitcnt lgkmcnt(1)
	v_add_f32_e32 v144, v128, v144
	v_cndmask_b32_e64 v144, v18, v144, s[94:95]
	s_waitcnt lgkmcnt(0)
	v_add_f32_e32 v145, v129, v145
	v_cndmask_b32_e64 v145, v18, v145, s[6:7]
	v_mov_b64_e32 v[114:115], v[130:131]
	v_mov_b64_e32 v[116:117], v[132:133]
	v_mov_b64_e32 v[118:119], v[134:135]
	v_mov_b64_e32 v[120:121], v[136:137]
	v_mov_b64_e32 v[122:123], v[138:139]
	v_mov_b64_e32 v[124:125], v[140:141]
	v_mov_b64_e32 v[126:127], v[142:143]
	v_mov_b64_e32 v[128:129], v[144:145]
	v_mov_b64_e32 v[144:145], v[112:113]
	v_mov_b64_e32 v[142:143], v[110:111]
	v_mov_b64_e32 v[140:141], v[108:109]
	v_mov_b64_e32 v[138:139], v[106:107]
	v_mov_b64_e32 v[136:137], v[104:105]
	v_mov_b64_e32 v[134:135], v[102:103]
	v_mov_b64_e32 v[132:133], v[100:101]
	v_mov_b64_e32 v[130:131], v[98:99]
